# norm_ctx (context-row norm): 9 loop-invariant gain/scale/shift loads hoisted to the loop top instead of 3 serialised load-wait-store rounds
# speedup vs baseline: 1.0037x; 1.0037x over previous
; __device__ __forceinline__ void norm_ctx(const Ctx& X, const float* ctx, const float* P, const float* gate8, const float* gain, const float* mod8, int si, bf16_t* HN) {
;     const float* sh = mod8 + si * 1024; const float* scl = sh + 1024;
;     for (int r = X.gw; r < MC; r += X.NGW) {
;         f32x4 v[4]; float s = 0.f;
; #pragma unroll
;         for (int j = 0; j < 4; ++j) { const int c = (X.lane + 64 * j) * 4; const size_t o = (size_t)r * D + c;
;             const f32x4 p = (*(const f32x4*)(P + o) + *(const f32x4*)(P + (size_t)MC * D + o)) + (*(const f32x4*)(P + (size_t)2 * MC * D + o) + *(const f32x4*)(P + (size_t)3 * MC * D + o));
;             v[j] = *(const f32x4*)(ctx + o) + *(const f32x4*)(gate8 + c) * 0.5f * p; s += (v[j].x * v[j].x + v[j].y * v[j].y) + (v[j].z * v[j].z + v[j].w * v[j].w); }
.LBB0_422:
	global_load_dwordx4 v[208:211], v[16:17], off
	global_load_dwordx4 v[212:215], v[18:19], off
	global_load_dwordx4 v[216:219], v[20:21], off
	global_load_dwordx4 v[220:223], v[22:23], off
	global_load_dwordx4 v[224:227], v[24:25], off
	global_load_dwordx4 v[228:231], v[26:27], off
	global_load_dwordx4 v[232:235], v[28:29], off
	global_load_dwordx4 v[236:239], v[30:31], off
	global_load_dwordx4 v[240:243], v[32:33], off
	v_lshl_add_u64 v[120:121], s[0:1], 0, v[0:1]
	v_add_co_u32_e32 v100, vcc, 0x17400000, v120
	v_lshl_add_u64 v[84:85], s[6:7], 0, v[0:1]
	s_nop 0
	v_addc_co_u32_e32 v101, vcc, 0, v121, vcc
	v_add_co_u32_e32 v116, vcc, 0x17c00000, v120
	global_load_dwordx4 v[44:47], v[2:3], off
	global_load_dwordx4 v[48:51], v[4:5], off
	global_load_dwordx4 v[52:55], v[6:7], off
	global_load_dwordx4 v[56:59], v[8:9], off
	v_addc_co_u32_e32 v117, vcc, 0, v121, vcc
	v_add_co_u32_e32 v132, vcc, 0x18400000, v120
	global_load_dwordx4 v[60:63], v[10:11], off
	global_load_dwordx4 v[64:67], v[12:13], off
	global_load_dwordx4 v[68:71], v[14:15], off
	v_addc_co_u32_e32 v133, vcc, 0, v121, vcc
	v_add_co_u32_e32 v148, vcc, 0x18c00000, v120
	global_load_dwordx4 v[72:75], v[84:85], off
	global_load_dwordx4 v[76:79], v[84:85], off offset:1024
	global_load_dwordx4 v[80:83], v[84:85], off offset:2048
	s_nop 0
	global_load_dwordx4 v[84:87], v[84:85], off offset:3072
	v_addc_co_u32_e32 v149, vcc, 0, v121, vcc
	global_load_dwordx4 v[88:91], v[100:101], off
	global_load_dwordx4 v[92:95], v[100:101], off offset:1024
	global_load_dwordx4 v[96:99], v[100:101], off offset:2048
	s_nop 0
	global_load_dwordx4 v[100:103], v[100:101], off offset:3072
	s_nop 0
	global_load_dwordx4 v[104:107], v[116:117], off
	global_load_dwordx4 v[108:111], v[116:117], off offset:1024
	global_load_dwordx4 v[112:115], v[116:117], off offset:2048
	s_nop 0
	global_load_dwordx4 v[116:119], v[116:117], off offset:3072
	s_nop 0
	global_load_dwordx4 v[120:123], v[132:133], off
	global_load_dwordx4 v[124:127], v[132:133], off offset:1024
	global_load_dwordx4 v[128:131], v[132:133], off offset:2048
	s_nop 0
	global_load_dwordx4 v[132:135], v[132:133], off offset:3072
	s_nop 0
	global_load_dwordx4 v[136:139], v[148:149], off
	global_load_dwordx4 v[140:143], v[148:149], off offset:1024
	global_load_dwordx4 v[144:147], v[148:149], off offset:2048
	s_nop 0
	global_load_dwordx4 v[148:151], v[148:149], off offset:3072
	s_add_i32 s10, s8, 0x8000
	s_ashr_i32 s11, s10, 31
	s_lshl_b64 s[10:11], s[10:11], 11
	v_lshl_add_u64 v[152:153], v[34:35], 0, s[10:11]
	s_add_i32 s8, s8, s20
	s_add_u32 s0, s0, s4
	s_addc_u32 s1, s1, s5
	s_add_u32 s6, s6, s4
	s_addc_u32 s7, s7, s5
	s_cmpk_lt_i32 s8, 0x800
	s_waitcnt vmcnt(26)
	v_pk_mul_f32 v[46:47], v[46:47], 0.5 op_sel_hi:[1,0]
	v_pk_mul_f32 v[44:45], v[44:45], 0.5 op_sel_hi:[1,0]
	s_waitcnt vmcnt(25)
	v_pk_mul_f32 v[50:51], v[50:51], 0.5 op_sel_hi:[1,0]
	v_pk_mul_f32 v[48:49], v[48:49], 0.5 op_sel_hi:[1,0]
	s_waitcnt vmcnt(24)
	v_pk_mul_f32 v[54:55], v[54:55], 0.5 op_sel_hi:[1,0]
	v_pk_mul_f32 v[52:53], v[52:53], 0.5 op_sel_hi:[1,0]
	s_waitcnt vmcnt(23)
	v_pk_mul_f32 v[56:57], v[56:57], 0.5 op_sel_hi:[1,0]
	v_pk_mul_f32 v[58:59], v[58:59], 0.5 op_sel_hi:[1,0]
	s_waitcnt vmcnt(21)
	v_pk_add_f32 v[64:65], v[64:65], 1.0 op_sel_hi:[1,0]
	v_pk_add_f32 v[66:67], v[66:67], 1.0 op_sel_hi:[1,0]
	s_waitcnt vmcnt(11)
	v_pk_add_f32 v[90:91], v[90:91], v[106:107]
	v_pk_add_f32 v[88:89], v[88:89], v[104:105]
	s_waitcnt vmcnt(10)
	v_pk_add_f32 v[94:95], v[94:95], v[110:111]
	v_pk_add_f32 v[92:93], v[92:93], v[108:109]
	s_waitcnt vmcnt(3)
	v_pk_add_f32 v[104:105], v[122:123], v[138:139]
	v_pk_add_f32 v[106:107], v[120:121], v[136:137]
	s_waitcnt vmcnt(2)
	v_pk_add_f32 v[108:109], v[126:127], v[142:143]
	v_pk_add_f32 v[110:111], v[124:125], v[140:141]
	v_pk_add_f32 v[98:99], v[98:99], v[114:115]
	v_pk_add_f32 v[96:97], v[96:97], v[112:113]
	s_waitcnt vmcnt(1)
	v_pk_add_f32 v[112:113], v[130:131], v[146:147]
	v_pk_add_f32 v[114:115], v[128:129], v[144:145]
	v_pk_add_f32 v[90:91], v[90:91], v[104:105]
	v_pk_add_f32 v[88:89], v[88:89], v[106:107]
	v_pk_add_f32 v[94:95], v[94:95], v[108:109]
	v_pk_add_f32 v[92:93], v[92:93], v[110:111]
	v_pk_add_f32 v[102:103], v[102:103], v[118:119]
	v_pk_add_f32 v[100:101], v[100:101], v[116:117]
	s_waitcnt vmcnt(0)
; __device__ __forceinline__ unsigned cvt_pk_bf16(float lo, float hi) { unsigned r; asm("v_cvt_pk_bf16_f32 %0, %1, %2" : "=v"(r) : "v"(lo), "v"(hi)); return r; }
; __device__ __forceinline__ void norm_ctx(const Ctx& X, const float* ctx, const float* P, const float* gate8, const float* gain, const float* mod8, int si, bf16_t* HN) {
;     ...
;         const float rstd = rsqrtf(wave_sum(s) * (1.0f / 1024.0f) + 1e-6f);
; #pragma unroll
;         for (int j = 0; j < 4; ++j) { const int c = (X.lane + 64 * j) * 4; const f32x4 gn = *(const f32x4*)(gain + c), a = *(const f32x4*)(scl + c), b = *(const f32x4*)(sh + c);
;             const f32x4 o = v[j] * rstd * gn * (a + 1.0f) + b; u32x2 w; w.x = cvt_pk_bf16(o.x, o.y); w.y = cvt_pk_bf16(o.z, o.w); *(u32x2*)(HN + (size_t)(MX + r) * D + c) = w; }
;     }
	v_pk_add_f32 v[118:119], v[132:133], v[148:149]
	v_pk_add_f32 v[98:99], v[98:99], v[112:113]
	v_pk_add_f32 v[96:97], v[96:97], v[114:115]
	v_pk_fma_f32 v[46:47], v[90:91], v[46:47], v[74:75]
	v_pk_fma_f32 v[44:45], v[88:89], v[44:45], v[72:73]
	v_pk_fma_f32 v[72:73], v[94:95], v[50:51], v[78:79]
	v_pk_fma_f32 v[74:75], v[92:93], v[48:49], v[76:77]
	v_pk_add_f32 v[116:117], v[134:135], v[150:151]
	v_pk_add_f32 v[100:101], v[100:101], v[118:119]
	v_pk_fma_f32 v[76:77], v[98:99], v[54:55], v[82:83]
	v_pk_fma_f32 v[78:79], v[96:97], v[52:53], v[80:81]
	v_pk_mul_f32 v[48:49], v[46:47], v[46:47]
	v_pk_mul_f32 v[50:51], v[44:45], v[44:45]
	v_pk_mul_f32 v[52:53], v[72:73], v[72:73]
	v_pk_mul_f32 v[54:55], v[74:75], v[74:75]
	v_pk_add_f32 v[102:103], v[102:103], v[116:117]
	v_pk_fma_f32 v[56:57], v[100:101], v[56:57], v[84:85]
	v_pk_mov_b32 v[84:85], v[50:51], v[48:49] op_sel:[1,0]
	v_mov_b32_e32 v51, v49
	v_pk_mov_b32 v[48:49], v[54:55], v[52:53] op_sel:[1,0]
	v_mov_b32_e32 v55, v53
	v_pk_fma_f32 v[58:59], v[102:103], v[58:59], v[86:87]
	v_mul_f32_e32 v83, v57, v57
	v_mul_f32_e32 v80, v79, v79
	v_mul_f32_e32 v82, v77, v77
	v_pk_add_f32 v[50:51], v[84:85], v[50:51]
	v_pk_add_f32 v[48:49], v[48:49], v[54:55]
	v_mul_f32_e32 v43, v56, v56
	v_mul_f32_e32 v86, v58, v58
	v_mul_f32_e32 v87, v59, v59
	v_pk_fma_f32 v[52:53], v[78:79], v[78:79], v[80:81] op_sel_hi:[1,1,0]
	v_pk_fma_f32 v[80:81], v[76:77], v[76:77], v[82:83] op_sel_hi:[1,1,0]
	v_pk_add_f32 v[50:51], v[50:51], v[50:51] op_sel:[0,1] op_sel_hi:[1,0]
	v_pk_add_f32 v[48:49], v[48:49], v[48:49] op_sel:[0,1] op_sel_hi:[1,0]
	v_mov_b32_e32 v53, v86
	v_mov_b32_e32 v81, v87
	v_mov_b32_e32 v51, v43
	v_mov_b32_e32 v49, v83
	v_pk_add_f32 v[52:53], v[52:53], v[80:81]
	v_pk_add_f32 v[48:49], v[50:51], v[48:49]
	s_nop 0
	v_pk_add_f32 v[48:49], v[48:49], v[52:53]
	s_nop 0
	v_add_f32_e32 v43, v48, v49
	ds_bpermute_b32 v48, v36, v43
	s_waitcnt lgkmcnt(0)
	v_add_f32_e32 v43, v43, v48
	ds_bpermute_b32 v48, v37, v43
	s_waitcnt lgkmcnt(0)
	v_add_f32_e32 v43, v43, v48
	ds_bpermute_b32 v48, v38, v43
	s_waitcnt lgkmcnt(0)
	v_add_f32_e32 v43, v43, v48
	ds_bpermute_b32 v48, v39, v43
	s_waitcnt lgkmcnt(0)
	v_add_f32_e32 v43, v43, v48
	ds_bpermute_b32 v48, v40, v43
	s_waitcnt lgkmcnt(0)
	v_add_f32_e32 v43, v43, v48
	ds_bpermute_b32 v48, v41, v43
	s_waitcnt lgkmcnt(0)
	v_add_f32_e32 v43, v43, v48
	v_fmamk_f32 v43, v43, 0x3a800000, v42
	v_mul_f32_e32 v48, 0x4b800000, v43
	v_cmp_gt_f32_e32 vcc, s9, v43
	s_nop 1
	v_cndmask_b32_e32 v43, v43, v48, vcc
	v_rsq_f32_e32 v43, v43
	s_nop 0
	v_mul_f32_e32 v48, 0x45800000, v43
	v_cndmask_b32_e32 v80, v43, v48, vcc
	v_pk_mul_f32 v[44:45], v[44:45], v[80:81] op_sel_hi:[1,0]
	v_pk_mul_f32 v[46:47], v[46:47], v[80:81] op_sel_hi:[1,0]
	v_pk_mul_f32 v[44:45], v[60:61], v[44:45]
	v_pk_mul_f32 v[46:47], v[62:63], v[46:47]
	v_pk_fma_f32 v[44:45], v[64:65], v[44:45], v[68:69]
	v_pk_fma_f32 v[46:47], v[66:67], v[46:47], v[70:71]
	v_cvt_pk_bf16_f32 v44, v44, v45
	v_pk_mul_f32 v[62:63], v[74:75], v[80:81] op_sel_hi:[1,0]
	v_cvt_pk_bf16_f32 v45, v46, v47
	global_store_dwordx2 v[152:153], v[44:45], off
	s_nop 1
	v_pk_mul_f32 v[60:61], v[72:73], v[80:81] op_sel_hi:[1,0]
	v_pk_mul_f32 v[56:57], v[56:57], v[80:81] op_sel_hi:[1,0]
	v_pk_mul_f32 v[58:59], v[58:59], v[80:81] op_sel_hi:[1,0]
	v_pk_mul_f32 v[44:45], v[208:209], v[62:63]
	v_pk_add_f32 v[48:49], v[212:213], 1.0 op_sel_hi:[1,0]
	v_pk_mul_f32 v[46:47], v[210:211], v[60:61]
	v_pk_add_f32 v[50:51], v[214:215], 1.0 op_sel_hi:[1,0]
	v_pk_fma_f32 v[44:45], v[48:49], v[44:45], v[216:217]
	v_pk_fma_f32 v[46:47], v[50:51], v[46:47], v[218:219]
	v_cvt_pk_bf16_f32 v44, v44, v45
	v_pk_mul_f32 v[62:63], v[78:79], v[80:81] op_sel_hi:[1,0]
	v_cvt_pk_bf16_f32 v45, v46, v47
	global_store_dwordx2 v[152:153], v[44:45], off offset:512
	s_nop 1
	v_pk_mul_f32 v[60:61], v[76:77], v[80:81] op_sel_hi:[1,0]
	v_pk_mul_f32 v[44:45], v[220:221], v[62:63]
	v_pk_add_f32 v[48:49], v[224:225], 1.0 op_sel_hi:[1,0]
	v_pk_mul_f32 v[46:47], v[222:223], v[60:61]
	v_pk_add_f32 v[50:51], v[226:227], 1.0 op_sel_hi:[1,0]
	v_pk_fma_f32 v[44:45], v[48:49], v[44:45], v[228:229]
	v_pk_fma_f32 v[46:47], v[50:51], v[46:47], v[230:231]
	v_cvt_pk_bf16_f32 v44, v44, v45
	s_nop 0
	v_cvt_pk_bf16_f32 v45, v46, v47
	global_store_dwordx2 v[152:153], v[44:45], off offset:1024
	s_nop 1
	v_pk_mul_f32 v[44:45], v[56:57], v[232:233]
	v_pk_add_f32 v[48:49], v[236:237], 1.0 op_sel_hi:[1,0]
	v_pk_mul_f32 v[46:47], v[58:59], v[234:235]
	v_pk_add_f32 v[50:51], v[238:239], 1.0 op_sel_hi:[1,0]
	v_pk_fma_f32 v[44:45], v[44:45], v[48:49], v[240:241]
	v_pk_fma_f32 v[46:47], v[46:47], v[50:51], v[242:243]
	v_cvt_pk_bf16_f32 v44, v44, v45
	s_nop 0
	v_cvt_pk_bf16_f32 v45, v46, v47
	global_store_dwordx2 v[152:153], v[44:45], off offset:1536
	s_cbranch_scc1 .LBB0_422
